# stacked latency trims on step22: header PART2 load batching + unit barrier arrival with the 8 early loads in flight (vmcnt 8) + no back-off sleep in the unit-barrier poll
# speedup vs baseline: 1.0028x; 1.0022x over previous
.Lfe0_bspin:
	global_load_dword v245, v242, s[62:63] offset:8 sc1
	s_waitcnt vmcnt(0)
	v_cmp_ge_u32_e32 vcc, v245, v244
	s_cbranch_vccnz .Lfe0_bdone
	s_nop 0
	s_add_u32 s94, s94, 1
	s_cmp_lt_u32 s94, 0x400000
	s_cbranch_scc1 .Lfe0_bspin

.Lfe2_bspin:
	global_load_dword v241, v238, s[62:63] offset:8 sc1
	s_waitcnt vmcnt(0)
	v_cmp_ge_u32_e32 vcc, v241, v240
	s_cbranch_vccnz .Lfe2_bdone
	s_nop 0
	s_add_u32 s94, s94, 1
	s_cmp_lt_u32 s94, 0x400000
	s_cbranch_scc1 .Lfe2_bspin

.Lp13_bspin:
	global_load_dword v247, v244, s[60:61] offset:8 sc1
	s_waitcnt vmcnt(0)
	v_cmp_ge_u32_e32 vcc, v247, v246
	s_cbranch_vccnz .Lp13_bdone
	s_nop 0
	s_add_u32 s59, s59, 1
	s_cmp_lt_u32 s59, 0x400000
	s_cbranch_scc1 .Lp13_bspin
